# idle-round weight conversion stores carry the streaming hint (v66 + convnt)
# baseline (speedup 1.0000x reference)
.LBB0_768:
	s_waitcnt vmcnt(1)
	v_mul_f32_e32 v157, v32, v186
	s_waitcnt vmcnt(0)
	v_mul_f32_e32 v159, v60, v187
	v_cvt_pk_bf16_f32 v157, v157, v159
	ds_write_b32 v149, v157 offset:112
	v_mul_f32_e32 v157, v33, v186
	v_mul_f32_e32 v159, v61, v187
	v_cvt_pk_bf16_f32 v157, v157, v159
	ds_write_b32 v149, v157 offset:244
	v_mul_f32_e32 v157, v34, v186
	v_mul_f32_e32 v159, v62, v187
	v_cvt_pk_bf16_f32 v157, v157, v159
	ds_write_b32 v149, v157 offset:376
	v_mul_f32_e32 v157, v35, v186
	v_mul_f32_e32 v159, v63, v187
	v_cvt_pk_bf16_f32 v157, v157, v159
	ds_write_b32 v149, v157 offset:508
	ds_read2_b32 v[186:187], v151 offset1:1
	ds_read2_b32 v[188:189], v151 offset0:2 offset1:3
	v_mad_u64_u32 v[190:191], s[6:7], s37, v130, 0
	v_lshl_add_u64 v[190:191], v[190:191], 1, s[10:11]
	ds_read2_b32 v[194:195], v153 offset1:1
	ds_read2_b32 v[196:197], v153 offset0:2 offset1:3
	v_lshl_add_u64 v[190:191], v[190:191], 0, v[166:167]
	s_waitcnt lgkmcnt(2)
	global_store_dwordx4 v[190:191], v[186:189], off nt
	v_cmp_gt_i32_e32 vcc, s38, v170
	s_nop 0
	v_mad_u64_u32 v[186:187], s[6:7], s37, v168, 0
	v_lshl_add_u64 v[186:187], v[186:187], 1, s[10:11]
	v_lshl_add_u64 v[186:187], v[186:187], 0, v[166:167]
	s_waitcnt lgkmcnt(0)
	global_store_dwordx4 v[186:187], v[194:197], off nt
	s_and_saveexec_b64 s[6:7], vcc
	s_cbranch_execz .LBB0_775
	v_add_u32_e32 v157, v135, v137
	ds_read2_b32 v[186:187], v157 offset1:1
	ds_read2_b32 v[188:189], v157 offset0:2 offset1:3
	v_mad_u64_u32 v[190:191], s[20:21], s37, v170, 0
	v_lshl_add_u64 v[190:191], v[190:191], 1, s[10:11]
	v_lshl_add_u64 v[190:191], v[190:191], 0, v[166:167]
	s_waitcnt lgkmcnt(0)
	global_store_dwordx4 v[190:191], v[186:189], off nt
	s_or_b64 exec, exec, s[6:7]
	v_cmp_gt_i32_e32 vcc, s38, v172
	s_and_saveexec_b64 s[6:7], vcc
	s_cbranch_execnz .LBB0_776

.LBB0_771:
	v_add_u32_e32 v157, v135, v141
	ds_read2_b32 v[186:187], v157 offset1:1
	ds_read2_b32 v[188:189], v157 offset0:2 offset1:3
	v_mad_u64_u32 v[190:191], s[20:21], s37, v174, 0
	v_lshl_add_u64 v[190:191], v[190:191], 1, s[10:11]
	v_lshl_add_u64 v[190:191], v[190:191], 0, v[166:167]
	s_waitcnt lgkmcnt(0)
	global_store_dwordx4 v[190:191], v[186:189], off nt
	s_or_b64 exec, exec, s[6:7]
	v_cmp_gt_i32_e32 vcc, s38, v176
	s_and_saveexec_b64 s[6:7], vcc
	s_cbranch_execnz .LBB0_778

.LBB0_773:
	v_add_u32_e32 v157, v135, v145
	ds_read2_b32 v[186:187], v157 offset1:1
	ds_read2_b32 v[188:189], v157 offset0:2 offset1:3
	v_mad_u64_u32 v[190:191], s[20:21], s37, v178, 0
	v_lshl_add_u64 v[190:191], v[190:191], 1, s[10:11]
	v_lshl_add_u64 v[190:191], v[190:191], 0, v[166:167]
	s_waitcnt lgkmcnt(0)
	global_store_dwordx4 v[190:191], v[186:189], off nt
	s_or_b64 exec, exec, s[6:7]
	v_cmp_gt_i32_e32 vcc, s38, v180
	s_and_saveexec_b64 s[6:7], vcc
	s_cbranch_execnz .LBB0_780

.LBB0_776:
	v_add_u32_e32 v157, v135, v139
	ds_read2_b32 v[186:187], v157 offset1:1
	ds_read2_b32 v[188:189], v157 offset0:2 offset1:3
	v_mad_u64_u32 v[190:191], s[20:21], s37, v172, 0
	v_lshl_add_u64 v[190:191], v[190:191], 1, s[10:11]
	v_lshl_add_u64 v[190:191], v[190:191], 0, v[166:167]
	s_waitcnt lgkmcnt(0)
	global_store_dwordx4 v[190:191], v[186:189], off nt
	s_or_b64 exec, exec, s[6:7]
	v_cmp_gt_i32_e32 vcc, s38, v174
	s_and_saveexec_b64 s[6:7], vcc
	s_cbranch_execnz .LBB0_771

.LBB0_778:
	v_add_u32_e32 v157, v135, v143
	ds_read2_b32 v[186:187], v157 offset1:1
	ds_read2_b32 v[188:189], v157 offset0:2 offset1:3
	v_mad_u64_u32 v[190:191], s[20:21], s37, v176, 0
	v_lshl_add_u64 v[190:191], v[190:191], 1, s[10:11]
	v_lshl_add_u64 v[190:191], v[190:191], 0, v[166:167]
	s_waitcnt lgkmcnt(0)
	global_store_dwordx4 v[190:191], v[186:189], off nt
	s_or_b64 exec, exec, s[6:7]
	v_cmp_gt_i32_e32 vcc, s38, v178
	s_and_saveexec_b64 s[6:7], vcc
	s_cbranch_execnz .LBB0_773

.LBB0_780:
	v_add_u32_e32 v157, v135, v147
	ds_read2_b32 v[186:187], v157 offset1:1
	ds_read2_b32 v[188:189], v157 offset0:2 offset1:3
	v_mad_u64_u32 v[190:191], s[20:21], s37, v180, 0
	v_lshl_add_u64 v[190:191], v[190:191], 1, s[10:11]
	v_lshl_add_u64 v[190:191], v[190:191], 0, v[166:167]
	s_waitcnt lgkmcnt(0)
	global_store_dwordx4 v[190:191], v[186:189], off nt
	s_or_b64 exec, exec, s[6:7]
	s_andn2_b64 vcc, exec, s[18:19]
	s_mov_b64 s[18:19], 0
	s_cbranch_vccnz .LBB0_708

.LBB0_841:
	s_nop 0
	v_mul_f32_e32 v155, v120, v186
	v_mul_f32_e32 v157, v124, v187
	v_cvt_pk_bf16_f32 v155, v155, v157
	ds_write_b32 v149, v155 offset:112
	v_mul_f32_e32 v155, v121, v186
	v_mul_f32_e32 v157, v125, v187
	v_cvt_pk_bf16_f32 v155, v155, v157
	ds_write_b32 v149, v155 offset:244
	v_mul_f32_e32 v155, v122, v186
	v_mul_f32_e32 v157, v126, v187
	v_cvt_pk_bf16_f32 v155, v155, v157
	ds_write_b32 v149, v155 offset:376
	v_mul_f32_e32 v155, v123, v186
	v_mul_f32_e32 v157, v127, v187
	v_cvt_pk_bf16_f32 v155, v155, v157
	ds_write_b32 v149, v155 offset:508
	ds_read2_b32 v[186:187], v151 offset1:1
	ds_read2_b32 v[188:189], v151 offset0:2 offset1:3
	v_mad_u64_u32 v[190:191], s[6:7], s41, v130, 0
	v_lshl_add_u64 v[190:191], v[190:191], 1, s[16:17]
	ds_read2_b32 v[194:195], v153 offset1:1
	ds_read2_b32 v[196:197], v153 offset0:2 offset1:3
	v_lshl_add_u64 v[190:191], v[190:191], 0, v[166:167]
	s_waitcnt lgkmcnt(2)
	global_store_dwordx4 v[190:191], v[186:189], off nt
	v_cmp_gt_i32_e32 vcc, s42, v170
	s_nop 0
	v_mad_u64_u32 v[186:187], s[6:7], s41, v168, 0
	v_lshl_add_u64 v[186:187], v[186:187], 1, s[16:17]
	v_lshl_add_u64 v[186:187], v[186:187], 0, v[166:167]
	s_waitcnt lgkmcnt(0)
	global_store_dwordx4 v[186:187], v[194:197], off nt
	s_and_saveexec_b64 s[6:7], vcc
	s_cbranch_execz .LBB0_847
	v_add_u32_e32 v155, v135, v137
	ds_read2_b32 v[186:187], v155 offset1:1
	ds_read2_b32 v[188:189], v155 offset0:2 offset1:3
	v_mad_u64_u32 v[190:191], s[20:21], s41, v170, 0
	v_lshl_add_u64 v[190:191], v[190:191], 1, s[16:17]
	v_lshl_add_u64 v[190:191], v[190:191], 0, v[166:167]
	s_waitcnt lgkmcnt(0)
	global_store_dwordx4 v[190:191], v[186:189], off nt
	s_or_b64 exec, exec, s[6:7]
	v_cmp_gt_i32_e32 vcc, s42, v172
	s_and_saveexec_b64 s[6:7], vcc
	s_cbranch_execnz .LBB0_848

.LBB0_844:
	v_add_u32_e32 v155, v135, v141
	ds_read2_b32 v[186:187], v155 offset1:1
	ds_read2_b32 v[188:189], v155 offset0:2 offset1:3
	v_mad_u64_u32 v[190:191], s[20:21], s41, v174, 0
	v_lshl_add_u64 v[190:191], v[190:191], 1, s[16:17]
	v_lshl_add_u64 v[190:191], v[190:191], 0, v[166:167]
	s_waitcnt lgkmcnt(0)
	global_store_dwordx4 v[190:191], v[186:189], off nt
	s_or_b64 exec, exec, s[6:7]
	v_cmp_gt_i32_e32 vcc, s42, v176
	s_and_saveexec_b64 s[6:7], vcc
	s_cbranch_execnz .LBB0_850

.LBB0_846:
	v_add_u32_e32 v155, v135, v145
	ds_read2_b32 v[186:187], v155 offset1:1
	ds_read2_b32 v[188:189], v155 offset0:2 offset1:3
	v_mad_u64_u32 v[190:191], s[20:21], s41, v178, 0
	v_lshl_add_u64 v[190:191], v[190:191], 1, s[16:17]
	v_lshl_add_u64 v[190:191], v[190:191], 0, v[166:167]
	s_waitcnt lgkmcnt(0)
	global_store_dwordx4 v[190:191], v[186:189], off nt
	s_or_b64 exec, exec, s[6:7]
	v_cmp_gt_i32_e32 vcc, s42, v180
	s_and_saveexec_b64 s[6:7], vcc
	s_cbranch_execz .LBB0_707
	s_branch .LBB0_852

.LBB0_848:
	v_add_u32_e32 v155, v135, v139
	ds_read2_b32 v[186:187], v155 offset1:1
	ds_read2_b32 v[188:189], v155 offset0:2 offset1:3
	v_mad_u64_u32 v[190:191], s[20:21], s41, v172, 0
	v_lshl_add_u64 v[190:191], v[190:191], 1, s[16:17]
	v_lshl_add_u64 v[190:191], v[190:191], 0, v[166:167]
	s_waitcnt lgkmcnt(0)
	global_store_dwordx4 v[190:191], v[186:189], off nt
	s_or_b64 exec, exec, s[6:7]
	v_cmp_gt_i32_e32 vcc, s42, v174
	s_and_saveexec_b64 s[6:7], vcc
	s_cbranch_execnz .LBB0_844

.LBB0_850:
	v_add_u32_e32 v155, v135, v143
	ds_read2_b32 v[186:187], v155 offset1:1
	ds_read2_b32 v[188:189], v155 offset0:2 offset1:3
	v_mad_u64_u32 v[190:191], s[20:21], s41, v176, 0
	v_lshl_add_u64 v[190:191], v[190:191], 1, s[16:17]
	v_lshl_add_u64 v[190:191], v[190:191], 0, v[166:167]
	s_waitcnt lgkmcnt(0)
	global_store_dwordx4 v[190:191], v[186:189], off nt
	s_or_b64 exec, exec, s[6:7]
	v_cmp_gt_i32_e32 vcc, s42, v178
	s_and_saveexec_b64 s[6:7], vcc
	s_cbranch_execnz .LBB0_846

.LBB0_852:
	v_add_u32_e32 v155, v135, v147
	ds_read2_b32 v[186:187], v155 offset1:1
	ds_read2_b32 v[188:189], v155 offset0:2 offset1:3
	v_mad_u64_u32 v[190:191], s[20:21], s41, v180, 0
	v_lshl_add_u64 v[190:191], v[190:191], 1, s[16:17]
	v_lshl_add_u64 v[190:191], v[190:191], 0, v[166:167]
	s_waitcnt lgkmcnt(0)
	global_store_dwordx4 v[190:191], v[186:189], off nt
	s_branch .LBB0_707

.LBB0_1026:
	s_waitcnt vmcnt(1)
	v_mul_f32_e32 v153, v32, v186
	s_waitcnt vmcnt(0)
	v_mul_f32_e32 v155, v60, v187
	v_cvt_pk_bf16_f32 v153, v153, v155
	ds_write_b32 v145, v153 offset:112
	v_mul_f32_e32 v153, v33, v186
	v_mul_f32_e32 v155, v61, v187
	v_cvt_pk_bf16_f32 v153, v153, v155
	ds_write_b32 v145, v153 offset:244
	v_mul_f32_e32 v153, v34, v186
	v_mul_f32_e32 v155, v62, v187
	v_cvt_pk_bf16_f32 v153, v153, v155
	ds_write_b32 v145, v153 offset:376
	v_mul_f32_e32 v153, v35, v186
	v_mul_f32_e32 v155, v63, v187
	v_cvt_pk_bf16_f32 v153, v153, v155
	ds_write_b32 v145, v153 offset:508
	ds_read2_b32 v[186:187], v147 offset1:1
	ds_read2_b32 v[188:189], v147 offset0:2 offset1:3
	v_mad_u64_u32 v[190:191], s[6:7], s37, v130, 0
	v_lshl_add_u64 v[190:191], v[190:191], 1, s[10:11]
	ds_read2_b32 v[194:195], v149 offset1:1
	ds_read2_b32 v[196:197], v149 offset0:2 offset1:3
	v_lshl_add_u64 v[190:191], v[190:191], 0, v[166:167]
	s_waitcnt lgkmcnt(2)
	global_store_dwordx4 v[190:191], v[186:189], off nt
	v_cmp_gt_i32_e32 vcc, s39, v170
	s_nop 0
	v_mad_u64_u32 v[186:187], s[6:7], s37, v168, 0
	v_lshl_add_u64 v[186:187], v[186:187], 1, s[10:11]
	v_lshl_add_u64 v[186:187], v[186:187], 0, v[166:167]
	s_waitcnt lgkmcnt(0)
	global_store_dwordx4 v[186:187], v[194:197], off nt
	s_and_saveexec_b64 s[6:7], vcc
	s_cbranch_execz .LBB0_1033
	v_add_u32_e32 v153, v129, v131
	ds_read2_b32 v[186:187], v153 offset1:1
	ds_read2_b32 v[188:189], v153 offset0:2 offset1:3
	v_mad_u64_u32 v[190:191], s[20:21], s37, v170, 0
	v_lshl_add_u64 v[190:191], v[190:191], 1, s[10:11]
	v_lshl_add_u64 v[190:191], v[190:191], 0, v[166:167]
	s_waitcnt lgkmcnt(0)
	global_store_dwordx4 v[190:191], v[186:189], off nt
	s_or_b64 exec, exec, s[6:7]
	v_cmp_gt_i32_e32 vcc, s39, v172
	s_and_saveexec_b64 s[6:7], vcc
	s_cbranch_execnz .LBB0_1034

.LBB0_1029:
	v_add_u32_e32 v153, v129, v137
	ds_read2_b32 v[186:187], v153 offset1:1
	ds_read2_b32 v[188:189], v153 offset0:2 offset1:3
	v_mad_u64_u32 v[190:191], s[20:21], s37, v174, 0
	v_lshl_add_u64 v[190:191], v[190:191], 1, s[10:11]
	v_lshl_add_u64 v[190:191], v[190:191], 0, v[166:167]
	s_waitcnt lgkmcnt(0)
	global_store_dwordx4 v[190:191], v[186:189], off nt
	s_or_b64 exec, exec, s[6:7]
	v_cmp_gt_i32_e32 vcc, s39, v176
	s_and_saveexec_b64 s[6:7], vcc
	s_cbranch_execnz .LBB0_1036

.LBB0_1031:
	v_add_u32_e32 v153, v129, v141
	ds_read2_b32 v[186:187], v153 offset1:1
	ds_read2_b32 v[188:189], v153 offset0:2 offset1:3
	v_mad_u64_u32 v[190:191], s[20:21], s37, v178, 0
	v_lshl_add_u64 v[190:191], v[190:191], 1, s[10:11]
	v_lshl_add_u64 v[190:191], v[190:191], 0, v[166:167]
	s_waitcnt lgkmcnt(0)
	global_store_dwordx4 v[190:191], v[186:189], off nt
	s_or_b64 exec, exec, s[6:7]
	v_cmp_gt_i32_e32 vcc, s39, v180
	s_and_saveexec_b64 s[6:7], vcc
	s_cbranch_execnz .LBB0_1038

.LBB0_1034:
	v_add_u32_e32 v153, v129, v135
	ds_read2_b32 v[186:187], v153 offset1:1
	ds_read2_b32 v[188:189], v153 offset0:2 offset1:3
	v_mad_u64_u32 v[190:191], s[20:21], s37, v172, 0
	v_lshl_add_u64 v[190:191], v[190:191], 1, s[10:11]
	v_lshl_add_u64 v[190:191], v[190:191], 0, v[166:167]
	s_waitcnt lgkmcnt(0)
	global_store_dwordx4 v[190:191], v[186:189], off nt
	s_or_b64 exec, exec, s[6:7]
	v_cmp_gt_i32_e32 vcc, s39, v174
	s_and_saveexec_b64 s[6:7], vcc
	s_cbranch_execnz .LBB0_1029

.LBB0_1036:
	v_add_u32_e32 v153, v129, v139
	ds_read2_b32 v[186:187], v153 offset1:1
	ds_read2_b32 v[188:189], v153 offset0:2 offset1:3
	v_mad_u64_u32 v[190:191], s[20:21], s37, v176, 0
	v_lshl_add_u64 v[190:191], v[190:191], 1, s[10:11]
	v_lshl_add_u64 v[190:191], v[190:191], 0, v[166:167]
	s_waitcnt lgkmcnt(0)
	global_store_dwordx4 v[190:191], v[186:189], off nt
	s_or_b64 exec, exec, s[6:7]
	v_cmp_gt_i32_e32 vcc, s39, v178
	s_and_saveexec_b64 s[6:7], vcc
	s_cbranch_execnz .LBB0_1031

.LBB0_1038:
	v_add_u32_e32 v153, v129, v143
	ds_read2_b32 v[186:187], v153 offset1:1
	ds_read2_b32 v[188:189], v153 offset0:2 offset1:3
	v_mad_u64_u32 v[190:191], s[20:21], s37, v180, 0
	v_lshl_add_u64 v[190:191], v[190:191], 1, s[10:11]
	v_lshl_add_u64 v[190:191], v[190:191], 0, v[166:167]
	s_waitcnt lgkmcnt(0)
	global_store_dwordx4 v[190:191], v[186:189], off nt
	s_or_b64 exec, exec, s[6:7]
	s_andn2_b64 vcc, exec, s[18:19]
	s_mov_b64 s[18:19], 0
	s_cbranch_vccnz .LBB0_966

.LBB0_1099:
	s_nop 0
	v_mul_f32_e32 v151, v120, v186
	v_mul_f32_e32 v153, v124, v187
	v_cvt_pk_bf16_f32 v151, v151, v153
	ds_write_b32 v145, v151 offset:112
	v_mul_f32_e32 v151, v121, v186
	v_mul_f32_e32 v153, v125, v187
	v_cvt_pk_bf16_f32 v151, v151, v153
	ds_write_b32 v145, v151 offset:244
	v_mul_f32_e32 v151, v122, v186
	v_mul_f32_e32 v153, v126, v187
	v_cvt_pk_bf16_f32 v151, v151, v153
	ds_write_b32 v145, v151 offset:376
	v_mul_f32_e32 v151, v123, v186
	v_mul_f32_e32 v153, v127, v187
	v_cvt_pk_bf16_f32 v151, v151, v153
	ds_write_b32 v145, v151 offset:508
	ds_read2_b32 v[186:187], v147 offset1:1
	ds_read2_b32 v[188:189], v147 offset0:2 offset1:3
	v_mad_u64_u32 v[190:191], s[6:7], s40, v130, 0
	v_lshl_add_u64 v[190:191], v[190:191], 1, s[16:17]
	ds_read2_b32 v[194:195], v149 offset1:1
	ds_read2_b32 v[196:197], v149 offset0:2 offset1:3
	v_lshl_add_u64 v[190:191], v[190:191], 0, v[166:167]
	s_waitcnt lgkmcnt(2)
	global_store_dwordx4 v[190:191], v[186:189], off nt
	v_cmp_gt_i32_e32 vcc, s41, v170
	s_nop 0
	v_mad_u64_u32 v[186:187], s[6:7], s40, v168, 0
	v_lshl_add_u64 v[186:187], v[186:187], 1, s[16:17]
	v_lshl_add_u64 v[186:187], v[186:187], 0, v[166:167]
	s_waitcnt lgkmcnt(0)
	global_store_dwordx4 v[186:187], v[194:197], off nt
	s_and_saveexec_b64 s[6:7], vcc
	s_cbranch_execz .LBB0_1105
	v_add_u32_e32 v151, v129, v131
	ds_read2_b32 v[186:187], v151 offset1:1
	ds_read2_b32 v[188:189], v151 offset0:2 offset1:3
	v_mad_u64_u32 v[190:191], s[20:21], s40, v170, 0
	v_lshl_add_u64 v[190:191], v[190:191], 1, s[16:17]
	v_lshl_add_u64 v[190:191], v[190:191], 0, v[166:167]
	s_waitcnt lgkmcnt(0)
	global_store_dwordx4 v[190:191], v[186:189], off nt
	s_or_b64 exec, exec, s[6:7]
	v_cmp_gt_i32_e32 vcc, s41, v172
	s_and_saveexec_b64 s[6:7], vcc
	s_cbranch_execnz .LBB0_1106

.LBB0_1102:
	v_add_u32_e32 v151, v129, v137
	ds_read2_b32 v[186:187], v151 offset1:1
	ds_read2_b32 v[188:189], v151 offset0:2 offset1:3
	v_mad_u64_u32 v[190:191], s[20:21], s40, v174, 0
	v_lshl_add_u64 v[190:191], v[190:191], 1, s[16:17]
	v_lshl_add_u64 v[190:191], v[190:191], 0, v[166:167]
	s_waitcnt lgkmcnt(0)
	global_store_dwordx4 v[190:191], v[186:189], off nt
	s_or_b64 exec, exec, s[6:7]
	v_cmp_gt_i32_e32 vcc, s41, v176
	s_and_saveexec_b64 s[6:7], vcc
	s_cbranch_execnz .LBB0_1108

.LBB0_1104:
	v_add_u32_e32 v151, v129, v141
	ds_read2_b32 v[186:187], v151 offset1:1
	ds_read2_b32 v[188:189], v151 offset0:2 offset1:3
	v_mad_u64_u32 v[190:191], s[20:21], s40, v178, 0
	v_lshl_add_u64 v[190:191], v[190:191], 1, s[16:17]
	v_lshl_add_u64 v[190:191], v[190:191], 0, v[166:167]
	s_waitcnt lgkmcnt(0)
	global_store_dwordx4 v[190:191], v[186:189], off nt
	s_or_b64 exec, exec, s[6:7]
	v_cmp_gt_i32_e32 vcc, s41, v180
	s_and_saveexec_b64 s[6:7], vcc
	s_cbranch_execz .LBB0_965
	s_branch .LBB0_1110

.LBB0_1106:
	v_add_u32_e32 v151, v129, v135
	ds_read2_b32 v[186:187], v151 offset1:1
	ds_read2_b32 v[188:189], v151 offset0:2 offset1:3
	v_mad_u64_u32 v[190:191], s[20:21], s40, v172, 0
	v_lshl_add_u64 v[190:191], v[190:191], 1, s[16:17]
	v_lshl_add_u64 v[190:191], v[190:191], 0, v[166:167]
	s_waitcnt lgkmcnt(0)
	global_store_dwordx4 v[190:191], v[186:189], off nt
	s_or_b64 exec, exec, s[6:7]
	v_cmp_gt_i32_e32 vcc, s41, v174
	s_and_saveexec_b64 s[6:7], vcc
	s_cbranch_execnz .LBB0_1102

.LBB0_1108:
	v_add_u32_e32 v151, v129, v139
	ds_read2_b32 v[186:187], v151 offset1:1
	ds_read2_b32 v[188:189], v151 offset0:2 offset1:3
	v_mad_u64_u32 v[190:191], s[20:21], s40, v176, 0
	v_lshl_add_u64 v[190:191], v[190:191], 1, s[16:17]
	v_lshl_add_u64 v[190:191], v[190:191], 0, v[166:167]
	s_waitcnt lgkmcnt(0)
	global_store_dwordx4 v[190:191], v[186:189], off nt
	s_or_b64 exec, exec, s[6:7]
	v_cmp_gt_i32_e32 vcc, s41, v178
	s_and_saveexec_b64 s[6:7], vcc
	s_cbranch_execnz .LBB0_1104

.LBB0_1110:
	v_add_u32_e32 v151, v129, v143
	ds_read2_b32 v[186:187], v151 offset1:1
	ds_read2_b32 v[188:189], v151 offset0:2 offset1:3
	v_mad_u64_u32 v[190:191], s[20:21], s40, v180, 0
	v_lshl_add_u64 v[190:191], v[190:191], 1, s[16:17]
	v_lshl_add_u64 v[190:191], v[190:191], 0, v[166:167]
	s_waitcnt lgkmcnt(0)
	global_store_dwordx4 v[190:191], v[186:189], off nt
	s_branch .LBB0_965

.LBB0_1603:
	s_waitcnt vmcnt(1)
	v_mul_f32_e32 v157, v32, v186
	s_waitcnt vmcnt(0)
	v_mul_f32_e32 v159, v60, v187
	v_cvt_pk_bf16_f32 v157, v157, v159
	ds_write_b32 v149, v157 offset:112
	v_mul_f32_e32 v157, v33, v186
	v_mul_f32_e32 v159, v61, v187
	v_cvt_pk_bf16_f32 v157, v157, v159
	ds_write_b32 v149, v157 offset:244
	v_mul_f32_e32 v157, v34, v186
	v_mul_f32_e32 v159, v62, v187
	v_cvt_pk_bf16_f32 v157, v157, v159
	ds_write_b32 v149, v157 offset:376
	v_mul_f32_e32 v157, v35, v186
	v_mul_f32_e32 v159, v63, v187
	v_cvt_pk_bf16_f32 v157, v157, v159
	ds_write_b32 v149, v157 offset:508
	ds_read2_b32 v[186:187], v151 offset1:1
	ds_read2_b32 v[188:189], v151 offset0:2 offset1:3
	v_mad_u64_u32 v[190:191], s[6:7], s35, v130, 0
	v_lshl_add_u64 v[190:191], v[190:191], 1, s[10:11]
	ds_read2_b32 v[194:195], v153 offset1:1
	ds_read2_b32 v[196:197], v153 offset0:2 offset1:3
	v_lshl_add_u64 v[190:191], v[190:191], 0, v[166:167]
	s_waitcnt lgkmcnt(2)
	global_store_dwordx4 v[190:191], v[186:189], off nt
	v_cmp_gt_i32_e32 vcc, s36, v170
	s_nop 0
	v_mad_u64_u32 v[186:187], s[6:7], s35, v168, 0
	v_lshl_add_u64 v[186:187], v[186:187], 1, s[10:11]
	v_lshl_add_u64 v[186:187], v[186:187], 0, v[166:167]
	s_waitcnt lgkmcnt(0)
	global_store_dwordx4 v[186:187], v[194:197], off nt
	s_and_saveexec_b64 s[6:7], vcc
	s_cbranch_execz .LBB0_1610
	v_add_u32_e32 v157, v135, v137
	ds_read2_b32 v[186:187], v157 offset1:1
	ds_read2_b32 v[188:189], v157 offset0:2 offset1:3
	v_mad_u64_u32 v[190:191], s[18:19], s35, v170, 0
	v_lshl_add_u64 v[190:191], v[190:191], 1, s[10:11]
	v_lshl_add_u64 v[190:191], v[190:191], 0, v[166:167]
	s_waitcnt lgkmcnt(0)
	global_store_dwordx4 v[190:191], v[186:189], off nt
	s_or_b64 exec, exec, s[6:7]
	v_cmp_gt_i32_e32 vcc, s36, v172
	s_and_saveexec_b64 s[6:7], vcc
	s_cbranch_execnz .LBB0_1611

.LBB0_1606:
	v_add_u32_e32 v157, v135, v141
	ds_read2_b32 v[186:187], v157 offset1:1
	ds_read2_b32 v[188:189], v157 offset0:2 offset1:3
	v_mad_u64_u32 v[190:191], s[18:19], s35, v174, 0
	v_lshl_add_u64 v[190:191], v[190:191], 1, s[10:11]
	v_lshl_add_u64 v[190:191], v[190:191], 0, v[166:167]
	s_waitcnt lgkmcnt(0)
	global_store_dwordx4 v[190:191], v[186:189], off nt
	s_or_b64 exec, exec, s[6:7]
	v_cmp_gt_i32_e32 vcc, s36, v176
	s_and_saveexec_b64 s[6:7], vcc
	s_cbranch_execnz .LBB0_1613

.LBB0_1608:
	v_add_u32_e32 v157, v135, v145
	ds_read2_b32 v[186:187], v157 offset1:1
	ds_read2_b32 v[188:189], v157 offset0:2 offset1:3
	v_mad_u64_u32 v[190:191], s[18:19], s35, v178, 0
	v_lshl_add_u64 v[190:191], v[190:191], 1, s[10:11]
	v_lshl_add_u64 v[190:191], v[190:191], 0, v[166:167]
	s_waitcnt lgkmcnt(0)
	global_store_dwordx4 v[190:191], v[186:189], off nt
	s_or_b64 exec, exec, s[6:7]
	v_cmp_gt_i32_e32 vcc, s36, v180
	s_and_saveexec_b64 s[6:7], vcc
	s_cbranch_execnz .LBB0_1615

.LBB0_1611:
	v_add_u32_e32 v157, v135, v139
	ds_read2_b32 v[186:187], v157 offset1:1
	ds_read2_b32 v[188:189], v157 offset0:2 offset1:3
	v_mad_u64_u32 v[190:191], s[18:19], s35, v172, 0
	v_lshl_add_u64 v[190:191], v[190:191], 1, s[10:11]
	v_lshl_add_u64 v[190:191], v[190:191], 0, v[166:167]
	s_waitcnt lgkmcnt(0)
	global_store_dwordx4 v[190:191], v[186:189], off nt
	s_or_b64 exec, exec, s[6:7]
	v_cmp_gt_i32_e32 vcc, s36, v174
	s_and_saveexec_b64 s[6:7], vcc
	s_cbranch_execnz .LBB0_1606

.LBB0_1613:
	v_add_u32_e32 v157, v135, v143
	ds_read2_b32 v[186:187], v157 offset1:1
	ds_read2_b32 v[188:189], v157 offset0:2 offset1:3
	v_mad_u64_u32 v[190:191], s[18:19], s35, v176, 0
	v_lshl_add_u64 v[190:191], v[190:191], 1, s[10:11]
	v_lshl_add_u64 v[190:191], v[190:191], 0, v[166:167]
	s_waitcnt lgkmcnt(0)
	global_store_dwordx4 v[190:191], v[186:189], off nt
	s_or_b64 exec, exec, s[6:7]
	v_cmp_gt_i32_e32 vcc, s36, v178
	s_and_saveexec_b64 s[6:7], vcc
	s_cbranch_execnz .LBB0_1608

.LBB0_1615:
	v_add_u32_e32 v157, v135, v147
	ds_read2_b32 v[186:187], v157 offset1:1
	ds_read2_b32 v[188:189], v157 offset0:2 offset1:3
	v_mad_u64_u32 v[190:191], s[18:19], s35, v180, 0
	v_lshl_add_u64 v[190:191], v[190:191], 1, s[10:11]
	v_lshl_add_u64 v[190:191], v[190:191], 0, v[166:167]
	s_waitcnt lgkmcnt(0)
	global_store_dwordx4 v[190:191], v[186:189], off nt
	s_or_b64 exec, exec, s[6:7]
	s_andn2_b64 vcc, exec, s[16:17]
	s_mov_b64 s[16:17], 0
	s_cbranch_vccnz .LBB0_1540

.LBB0_1679:
	s_nop 0
	v_mul_f32_e32 v155, v120, v186
	v_mul_f32_e32 v157, v124, v187
	v_cvt_pk_bf16_f32 v155, v155, v157
	ds_write_b32 v149, v155 offset:112
	v_mul_f32_e32 v155, v121, v186
	v_mul_f32_e32 v157, v125, v187
	v_cvt_pk_bf16_f32 v155, v155, v157
	ds_write_b32 v149, v155 offset:244
	v_mul_f32_e32 v155, v122, v186
	v_mul_f32_e32 v157, v126, v187
	v_cvt_pk_bf16_f32 v155, v155, v157
	ds_write_b32 v149, v155 offset:376
	v_mul_f32_e32 v155, v123, v186
	v_mul_f32_e32 v157, v127, v187
	v_cvt_pk_bf16_f32 v155, v155, v157
	ds_write_b32 v149, v155 offset:508
	ds_read2_b32 v[186:187], v151 offset1:1
	ds_read2_b32 v[188:189], v151 offset0:2 offset1:3
	v_mad_u64_u32 v[190:191], s[6:7], s38, v130, 0
	v_lshl_add_u64 v[190:191], v[190:191], 1, s[14:15]
	ds_read2_b32 v[194:195], v153 offset1:1
	ds_read2_b32 v[196:197], v153 offset0:2 offset1:3
	v_lshl_add_u64 v[190:191], v[190:191], 0, v[166:167]
	s_waitcnt lgkmcnt(2)
	global_store_dwordx4 v[190:191], v[186:189], off nt
	v_cmp_gt_i32_e32 vcc, s40, v170
	s_nop 0
	v_mad_u64_u32 v[186:187], s[6:7], s38, v168, 0
	v_lshl_add_u64 v[186:187], v[186:187], 1, s[14:15]
	v_lshl_add_u64 v[186:187], v[186:187], 0, v[166:167]
	s_waitcnt lgkmcnt(0)
	global_store_dwordx4 v[186:187], v[194:197], off nt
	s_and_saveexec_b64 s[6:7], vcc
	s_cbranch_execz .LBB0_1685
	v_add_u32_e32 v155, v135, v137
	ds_read2_b32 v[186:187], v155 offset1:1
	ds_read2_b32 v[188:189], v155 offset0:2 offset1:3
	v_mad_u64_u32 v[190:191], s[18:19], s38, v170, 0
	v_lshl_add_u64 v[190:191], v[190:191], 1, s[14:15]
	v_lshl_add_u64 v[190:191], v[190:191], 0, v[166:167]
	s_waitcnt lgkmcnt(0)
	global_store_dwordx4 v[190:191], v[186:189], off nt
	s_or_b64 exec, exec, s[6:7]
	v_cmp_gt_i32_e32 vcc, s40, v172
	s_and_saveexec_b64 s[6:7], vcc
	s_cbranch_execnz .LBB0_1686

.LBB0_1682:
	v_add_u32_e32 v155, v135, v141
	ds_read2_b32 v[186:187], v155 offset1:1
	ds_read2_b32 v[188:189], v155 offset0:2 offset1:3
	v_mad_u64_u32 v[190:191], s[18:19], s38, v174, 0
	v_lshl_add_u64 v[190:191], v[190:191], 1, s[14:15]
	v_lshl_add_u64 v[190:191], v[190:191], 0, v[166:167]
	s_waitcnt lgkmcnt(0)
	global_store_dwordx4 v[190:191], v[186:189], off nt
	s_or_b64 exec, exec, s[6:7]
	v_cmp_gt_i32_e32 vcc, s40, v176
	s_and_saveexec_b64 s[6:7], vcc
	s_cbranch_execnz .LBB0_1688

.LBB0_1684:
	v_add_u32_e32 v155, v135, v145
	ds_read2_b32 v[186:187], v155 offset1:1
	ds_read2_b32 v[188:189], v155 offset0:2 offset1:3
	v_mad_u64_u32 v[190:191], s[18:19], s38, v178, 0
	v_lshl_add_u64 v[190:191], v[190:191], 1, s[14:15]
	v_lshl_add_u64 v[190:191], v[190:191], 0, v[166:167]
	s_waitcnt lgkmcnt(0)
	global_store_dwordx4 v[190:191], v[186:189], off nt
	s_or_b64 exec, exec, s[6:7]
	v_cmp_gt_i32_e32 vcc, s40, v180
	s_and_saveexec_b64 s[6:7], vcc
	s_cbranch_execz .LBB0_1539
	s_branch .LBB0_1690

.LBB0_1686:
	v_add_u32_e32 v155, v135, v139
	ds_read2_b32 v[186:187], v155 offset1:1
	ds_read2_b32 v[188:189], v155 offset0:2 offset1:3
	v_mad_u64_u32 v[190:191], s[18:19], s38, v172, 0
	v_lshl_add_u64 v[190:191], v[190:191], 1, s[14:15]
	v_lshl_add_u64 v[190:191], v[190:191], 0, v[166:167]
	s_waitcnt lgkmcnt(0)
	global_store_dwordx4 v[190:191], v[186:189], off nt
	s_or_b64 exec, exec, s[6:7]
	v_cmp_gt_i32_e32 vcc, s40, v174
	s_and_saveexec_b64 s[6:7], vcc
	s_cbranch_execnz .LBB0_1682

.LBB0_1688:
	v_add_u32_e32 v155, v135, v143
	ds_read2_b32 v[186:187], v155 offset1:1
	ds_read2_b32 v[188:189], v155 offset0:2 offset1:3
	v_mad_u64_u32 v[190:191], s[18:19], s38, v176, 0
	v_lshl_add_u64 v[190:191], v[190:191], 1, s[14:15]
	v_lshl_add_u64 v[190:191], v[190:191], 0, v[166:167]
	s_waitcnt lgkmcnt(0)
	global_store_dwordx4 v[190:191], v[186:189], off nt
	s_or_b64 exec, exec, s[6:7]
	v_cmp_gt_i32_e32 vcc, s40, v178
	s_and_saveexec_b64 s[6:7], vcc
	s_cbranch_execnz .LBB0_1684

.LBB0_1690:
	v_add_u32_e32 v155, v135, v147
	ds_read2_b32 v[186:187], v155 offset1:1
	ds_read2_b32 v[188:189], v155 offset0:2 offset1:3
	v_mad_u64_u32 v[190:191], s[18:19], s38, v180, 0
	v_lshl_add_u64 v[190:191], v[190:191], 1, s[14:15]
	v_lshl_add_u64 v[190:191], v[190:191], 0, v[166:167]
	s_waitcnt lgkmcnt(0)
	global_store_dwordx4 v[190:191], v[186:189], off nt
	s_branch .LBB0_1539

.LBB0_1846:
	s_waitcnt vmcnt(1)
	v_mul_f32_e32 v153, v32, v186
	s_waitcnt vmcnt(0)
	v_mul_f32_e32 v155, v60, v187
	v_cvt_pk_bf16_f32 v153, v153, v155
	ds_write_b32 v145, v153 offset:112
	v_mul_f32_e32 v153, v33, v186
	v_mul_f32_e32 v155, v61, v187
	v_cvt_pk_bf16_f32 v153, v153, v155
	ds_write_b32 v145, v153 offset:244
	v_mul_f32_e32 v153, v34, v186
	v_mul_f32_e32 v155, v62, v187
	v_cvt_pk_bf16_f32 v153, v153, v155
	ds_write_b32 v145, v153 offset:376
	v_mul_f32_e32 v153, v35, v186
	v_mul_f32_e32 v155, v63, v187
	v_cvt_pk_bf16_f32 v153, v153, v155
	ds_write_b32 v145, v153 offset:508
	ds_read2_b32 v[186:187], v147 offset1:1
	ds_read2_b32 v[188:189], v147 offset0:2 offset1:3
	v_mad_u64_u32 v[190:191], s[6:7], s35, v130, 0
	v_lshl_add_u64 v[190:191], v[190:191], 1, s[10:11]
	ds_read2_b32 v[194:195], v149 offset1:1
	ds_read2_b32 v[196:197], v149 offset0:2 offset1:3
	v_lshl_add_u64 v[190:191], v[190:191], 0, v[166:167]
	s_waitcnt lgkmcnt(2)
	global_store_dwordx4 v[190:191], v[186:189], off nt
	v_cmp_gt_i32_e32 vcc, s37, v170
	s_nop 0
	v_mad_u64_u32 v[186:187], s[6:7], s35, v168, 0
	v_lshl_add_u64 v[186:187], v[186:187], 1, s[10:11]
	v_lshl_add_u64 v[186:187], v[186:187], 0, v[166:167]
	s_waitcnt lgkmcnt(0)
	global_store_dwordx4 v[186:187], v[194:197], off nt
	s_and_saveexec_b64 s[6:7], vcc
	s_cbranch_execz .LBB0_1853
	v_add_u32_e32 v153, v129, v131
	ds_read2_b32 v[186:187], v153 offset1:1
	ds_read2_b32 v[188:189], v153 offset0:2 offset1:3
	v_mad_u64_u32 v[190:191], s[18:19], s35, v170, 0
	v_lshl_add_u64 v[190:191], v[190:191], 1, s[10:11]
	v_lshl_add_u64 v[190:191], v[190:191], 0, v[166:167]
	s_waitcnt lgkmcnt(0)
	global_store_dwordx4 v[190:191], v[186:189], off nt
	s_or_b64 exec, exec, s[6:7]
	v_cmp_gt_i32_e32 vcc, s37, v172
	s_and_saveexec_b64 s[6:7], vcc
	s_cbranch_execnz .LBB0_1854

.LBB0_1849:
	v_add_u32_e32 v153, v129, v137
	ds_read2_b32 v[186:187], v153 offset1:1
	ds_read2_b32 v[188:189], v153 offset0:2 offset1:3
	v_mad_u64_u32 v[190:191], s[18:19], s35, v174, 0
	v_lshl_add_u64 v[190:191], v[190:191], 1, s[10:11]
	v_lshl_add_u64 v[190:191], v[190:191], 0, v[166:167]
	s_waitcnt lgkmcnt(0)
	global_store_dwordx4 v[190:191], v[186:189], off nt
	s_or_b64 exec, exec, s[6:7]
	v_cmp_gt_i32_e32 vcc, s37, v176
	s_and_saveexec_b64 s[6:7], vcc
	s_cbranch_execnz .LBB0_1856

.LBB0_1851:
	v_add_u32_e32 v153, v129, v141
	ds_read2_b32 v[186:187], v153 offset1:1
	ds_read2_b32 v[188:189], v153 offset0:2 offset1:3
	v_mad_u64_u32 v[190:191], s[18:19], s35, v178, 0
	v_lshl_add_u64 v[190:191], v[190:191], 1, s[10:11]
	v_lshl_add_u64 v[190:191], v[190:191], 0, v[166:167]
	s_waitcnt lgkmcnt(0)
	global_store_dwordx4 v[190:191], v[186:189], off nt
	s_or_b64 exec, exec, s[6:7]
	v_cmp_gt_i32_e32 vcc, s37, v180
	s_and_saveexec_b64 s[6:7], vcc
	s_cbranch_execnz .LBB0_1858

.LBB0_1854:
	v_add_u32_e32 v153, v129, v135
	ds_read2_b32 v[186:187], v153 offset1:1
	ds_read2_b32 v[188:189], v153 offset0:2 offset1:3
	v_mad_u64_u32 v[190:191], s[18:19], s35, v172, 0
	v_lshl_add_u64 v[190:191], v[190:191], 1, s[10:11]
	v_lshl_add_u64 v[190:191], v[190:191], 0, v[166:167]
	s_waitcnt lgkmcnt(0)
	global_store_dwordx4 v[190:191], v[186:189], off nt
	s_or_b64 exec, exec, s[6:7]
	v_cmp_gt_i32_e32 vcc, s37, v174
	s_and_saveexec_b64 s[6:7], vcc
	s_cbranch_execnz .LBB0_1849

.LBB0_1856:
	v_add_u32_e32 v153, v129, v139
	ds_read2_b32 v[186:187], v153 offset1:1
	ds_read2_b32 v[188:189], v153 offset0:2 offset1:3
	v_mad_u64_u32 v[190:191], s[18:19], s35, v176, 0
	v_lshl_add_u64 v[190:191], v[190:191], 1, s[10:11]
	v_lshl_add_u64 v[190:191], v[190:191], 0, v[166:167]
	s_waitcnt lgkmcnt(0)
	global_store_dwordx4 v[190:191], v[186:189], off nt
	s_or_b64 exec, exec, s[6:7]
	v_cmp_gt_i32_e32 vcc, s37, v178
	s_and_saveexec_b64 s[6:7], vcc
	s_cbranch_execnz .LBB0_1851

.LBB0_1858:
	v_add_u32_e32 v153, v129, v143
	ds_read2_b32 v[186:187], v153 offset1:1
	ds_read2_b32 v[188:189], v153 offset0:2 offset1:3
	v_mad_u64_u32 v[190:191], s[18:19], s35, v180, 0
	v_lshl_add_u64 v[190:191], v[190:191], 1, s[10:11]
	v_lshl_add_u64 v[190:191], v[190:191], 0, v[166:167]
	s_waitcnt lgkmcnt(0)
	global_store_dwordx4 v[190:191], v[186:189], off nt
	s_or_b64 exec, exec, s[6:7]
	s_andn2_b64 vcc, exec, s[16:17]
	s_mov_b64 s[16:17], 0
	s_cbranch_vccnz .LBB0_1783

.LBB0_1922:
	s_nop 0
	v_mul_f32_e32 v151, v120, v186
	v_mul_f32_e32 v153, v124, v187
	v_cvt_pk_bf16_f32 v151, v151, v153
	ds_write_b32 v145, v151 offset:112
	v_mul_f32_e32 v151, v121, v186
	v_mul_f32_e32 v153, v125, v187
	v_cvt_pk_bf16_f32 v151, v151, v153
	ds_write_b32 v145, v151 offset:244
	v_mul_f32_e32 v151, v122, v186
	v_mul_f32_e32 v153, v126, v187
	v_cvt_pk_bf16_f32 v151, v151, v153
	ds_write_b32 v145, v151 offset:376
	v_mul_f32_e32 v151, v123, v186
	v_mul_f32_e32 v153, v127, v187
	v_cvt_pk_bf16_f32 v151, v151, v153
	ds_write_b32 v145, v151 offset:508
	ds_read2_b32 v[186:187], v147 offset1:1
	ds_read2_b32 v[188:189], v147 offset0:2 offset1:3
	v_mad_u64_u32 v[190:191], s[6:7], s34, v130, 0
	v_lshl_add_u64 v[190:191], v[190:191], 1, s[14:15]
	ds_read2_b32 v[194:195], v149 offset1:1
	ds_read2_b32 v[196:197], v149 offset0:2 offset1:3
	v_lshl_add_u64 v[190:191], v[190:191], 0, v[166:167]
	s_waitcnt lgkmcnt(2)
	global_store_dwordx4 v[190:191], v[186:189], off nt
	v_cmp_gt_i32_e32 vcc, s39, v170
	s_nop 0
	v_mad_u64_u32 v[186:187], s[6:7], s34, v168, 0
	v_lshl_add_u64 v[186:187], v[186:187], 1, s[14:15]
	v_lshl_add_u64 v[186:187], v[186:187], 0, v[166:167]
	s_waitcnt lgkmcnt(0)
	global_store_dwordx4 v[186:187], v[194:197], off nt
	s_and_saveexec_b64 s[6:7], vcc
	s_cbranch_execz .LBB0_1928
	v_add_u32_e32 v151, v129, v131
	ds_read2_b32 v[186:187], v151 offset1:1
	ds_read2_b32 v[188:189], v151 offset0:2 offset1:3
	v_mad_u64_u32 v[190:191], s[18:19], s34, v170, 0
	v_lshl_add_u64 v[190:191], v[190:191], 1, s[14:15]
	v_lshl_add_u64 v[190:191], v[190:191], 0, v[166:167]
	s_waitcnt lgkmcnt(0)
	global_store_dwordx4 v[190:191], v[186:189], off nt
	s_or_b64 exec, exec, s[6:7]
	v_cmp_gt_i32_e32 vcc, s39, v172
	s_and_saveexec_b64 s[6:7], vcc
	s_cbranch_execnz .LBB0_1929

.LBB0_1925:
	v_add_u32_e32 v151, v129, v137
	ds_read2_b32 v[186:187], v151 offset1:1
	ds_read2_b32 v[188:189], v151 offset0:2 offset1:3
	v_mad_u64_u32 v[190:191], s[18:19], s34, v174, 0
	v_lshl_add_u64 v[190:191], v[190:191], 1, s[14:15]
	v_lshl_add_u64 v[190:191], v[190:191], 0, v[166:167]
	s_waitcnt lgkmcnt(0)
	global_store_dwordx4 v[190:191], v[186:189], off nt
	s_or_b64 exec, exec, s[6:7]
	v_cmp_gt_i32_e32 vcc, s39, v176
	s_and_saveexec_b64 s[6:7], vcc
	s_cbranch_execnz .LBB0_1931

.LBB0_1927:
	v_add_u32_e32 v151, v129, v141
	ds_read2_b32 v[186:187], v151 offset1:1
	ds_read2_b32 v[188:189], v151 offset0:2 offset1:3
	v_mad_u64_u32 v[190:191], s[18:19], s34, v178, 0
	v_lshl_add_u64 v[190:191], v[190:191], 1, s[14:15]
	v_lshl_add_u64 v[190:191], v[190:191], 0, v[166:167]
	s_waitcnt lgkmcnt(0)
	global_store_dwordx4 v[190:191], v[186:189], off nt
	s_or_b64 exec, exec, s[6:7]
	v_cmp_gt_i32_e32 vcc, s39, v180
	s_and_saveexec_b64 s[6:7], vcc
	s_cbranch_execz .LBB0_1782
	s_branch .LBB0_1933

.LBB0_1929:
	v_add_u32_e32 v151, v129, v135
	ds_read2_b32 v[186:187], v151 offset1:1
	ds_read2_b32 v[188:189], v151 offset0:2 offset1:3
	v_mad_u64_u32 v[190:191], s[18:19], s34, v172, 0
	v_lshl_add_u64 v[190:191], v[190:191], 1, s[14:15]
	v_lshl_add_u64 v[190:191], v[190:191], 0, v[166:167]
	s_waitcnt lgkmcnt(0)
	global_store_dwordx4 v[190:191], v[186:189], off nt
	s_or_b64 exec, exec, s[6:7]
	v_cmp_gt_i32_e32 vcc, s39, v174
	s_and_saveexec_b64 s[6:7], vcc
	s_cbranch_execnz .LBB0_1925

.LBB0_1931:
	v_add_u32_e32 v151, v129, v139
	ds_read2_b32 v[186:187], v151 offset1:1
	ds_read2_b32 v[188:189], v151 offset0:2 offset1:3
	v_mad_u64_u32 v[190:191], s[18:19], s34, v176, 0
	v_lshl_add_u64 v[190:191], v[190:191], 1, s[14:15]
	v_lshl_add_u64 v[190:191], v[190:191], 0, v[166:167]
	s_waitcnt lgkmcnt(0)
	global_store_dwordx4 v[190:191], v[186:189], off nt
	s_or_b64 exec, exec, s[6:7]
	v_cmp_gt_i32_e32 vcc, s39, v178
	s_and_saveexec_b64 s[6:7], vcc
	s_cbranch_execnz .LBB0_1927

.LBB0_1933:
	v_add_u32_e32 v151, v129, v143
	ds_read2_b32 v[186:187], v151 offset1:1
	ds_read2_b32 v[188:189], v151 offset0:2 offset1:3
	v_mad_u64_u32 v[190:191], s[18:19], s34, v180, 0
	v_lshl_add_u64 v[190:191], v[190:191], 1, s[14:15]
	v_lshl_add_u64 v[190:191], v[190:191], 0, v[166:167]
	s_waitcnt lgkmcnt(0)
	global_store_dwordx4 v[190:191], v[186:189], off nt
	s_branch .LBB0_1782
